# v63 + one 4-byte pad at the FF1 phase entry: flips the byte phase (mod 8) of every hot loop from FF1 onward
# speedup vs baseline: 1.0003x; 1.0003x over previous
.LBB0_197:
	v_readlane_b32 s2, v237, 15
	s_waitcnt vmcnt(0)
	v_mov_b32_e32 v18, v190
	v_readlane_b32 s3, v237, 16
	s_movk_i32 s42, 0x400
	v_readfirstlane_b32 s31, v18
	s_movk_i32 s38, 0x400
	s_andn2_b64 vcc, exec, s[2:3]
	s_cbranch_vccnz .LBB0_219
	s_nop 0
	v_lshlrev_b32_e32 v0, 4, v18
	v_add_u32_e32 v2, 0x2000, v0
	s_waitcnt lgkmcnt(0)
	v_ashrrev_i32_e32 v3, 31, v2
	v_lshrrev_b32_e32 v3, 22, v3
	v_add_u32_e32 v3, v2, v3
	v_ashrrev_i32_e32 v3, 10, v3
	v_mul_i32_i24_e32 v4, 0x400, v3
	v_sub_u32_e32 v2, v2, v4
	v_lshrrev_b32_e32 v4, 4, v2
	v_bitop3_b32 v2, v4, v2, 32 bitop3:0x6c
	v_ashrrev_i32_e32 v4, 31, v2
	v_lshrrev_b32_e32 v4, 26, v4
	v_add_u32_e32 v4, v2, v4
	v_lshlrev_b32_e32 v6, 3, v3
	v_ashrrev_i32_e32 v5, 6, v4
	v_and_b32_e32 v6, -16, v6
	v_lshlrev_b32_e32 v3, 5, v3
	s_lshl_b32 s4, s97, 3
	v_readlane_b32 s27, v236, 12
	v_add_u32_e32 v6, v5, v6
	v_and_b32_e32 v20, 32, v3
	v_and_b32_e32 v3, 0xc0, v4
	s_or_b32 s54, s4, s27
	v_and_b32_e32 v5, 3, v5
	s_mov_b32 s27, 0x7fffffe0
	v_lshrrev_b32_e32 v7, 2, v6
	v_lshlrev_b32_e32 v8, 1, v6
	v_sub_u32_e32 v2, v2, v3
	v_and_or_b32 v5, v6, s27, v5
	v_and_b32_e32 v7, 4, v7
	v_and_b32_e32 v8, 24, v8
	v_ashrrev_i16_sdwa v2, v193, sext(v2) dst_sel:DWORD dst_unused:UNUSED_PAD src0_sel:DWORD src1_sel:BYTE_0
	v_or3_b32 v5, v5, v7, v8
	v_bfe_i32 v21, v2, 0, 16
	v_mul_lo_u32 v5, v5, s42
	v_add_u32_e32 v2, v20, v21
	v_mul_lo_u32 v22, v6, s38
	v_add_lshl_u32 v130, v5, v2, 1
	v_add_lshl_u32 v132, v2, v22, 1
	v_bfe_i32 v2, v18, 27, 1
	v_lshrrev_b32_e32 v2, 22, v2
	v_add_u32_e32 v2, v0, v2
	v_and_b32_e32 v2, 0xfffffc00, v2
	v_sub_u32_e32 v0, v0, v2
	v_lshrrev_b32_e32 v2, 4, v0
	v_ashrrev_i32_e32 v19, 31, v18
	v_bitop3_b32 v2, v2, v0, 32 bitop3:0x6c
	v_lshrrev_b32_e32 v4, 26, v19
	v_ashrrev_i32_e32 v0, 31, v2
	v_add_u32_e32 v4, v18, v4
	v_lshrrev_b32_e32 v0, 26, v0
	v_ashrrev_i32_e32 v4, 6, v4
	v_add_u32_e32 v3, v2, v0
	v_lshlrev_b32_e32 v5, 3, v4
	v_ashrrev_i32_e32 v0, 6, v3
	v_and_b32_e32 v5, -16, v5
	s_ashr_i32 s43, s42, 31
	v_add_u32_e32 v5, v0, v5
	v_readlane_b32 s40, v236, 24
	s_ashr_i32 s39, s38, 31
	s_lshl_b64 s[34:35], s[42:43], 9
	v_and_b32_e32 v0, 3, v0
	v_lshrrev_b32_e32 v6, 2, v5
	v_lshlrev_b32_e32 v7, 1, v5
	v_readlane_b32 s41, v236, 25
	s_lshl_b64 s[2:3], s[38:39], 8
	v_and_or_b32 v0, v5, s27, v0
	v_and_b32_e32 v6, 4, v6
	v_and_b32_e32 v7, 24, v7
	v_and_b32_e32 v3, 0xc0, v3
	v_mul_lo_u32 v24, v5, s38
	s_mul_i32 s27, s34, s41
	s_mul_hi_u32 s30, s34, s40
	s_lshr_b64 s[38:39], s[42:43], 23
	s_ashr_i32 s46, s31, 6
	v_or3_b32 v0, v0, v6, v7
	v_sub_u32_e32 v2, v2, v3
	s_ashr_i32 s55, s54, 31
	s_add_i32 s27, s30, s27
	s_mul_i32 s30, s38, s40
	s_lshl_b64 s[6:7], s[42:43], 8
	s_lshl_b32 s5, s46, 10
	v_mul_lo_u32 v6, v0, s42
	v_lshlrev_b32_e32 v0, 5, v4
	v_ashrrev_i16_sdwa v2, v193, sext(v2) dst_sel:DWORD dst_unused:UNUSED_PAD src0_sel:DWORD src1_sel:BYTE_0
	s_lshl_b64 s[28:29], s[54:55], 19
	s_add_i32 s27, s27, s30
	s_mul_i32 s30, s34, s40
	v_readlane_b32 s38, v235, 15
	v_and_b32_e32 v0, 32, v0
	v_bfe_i32 v23, v2, 0, 16
	s_add_u32 s58, s38, s30
	v_readlane_b32 s30, v235, 16
	v_add_u32_e32 v2, v0, v23
	s_addc_u32 s59, s30, s27
	s_add_i32 s27, s5, 0
	v_add_lshl_u32 v134, v6, v2, 1
	s_add_i32 m0, s27, 0x10000
	v_add_lshl_u32 v136, v2, v24, 1
	global_load_lds_dwordx4 v134, s[58:59]
	s_add_i32 m0, s27, 0x12000
	s_add_u32 s44, s58, s6
	global_load_lds_dwordx4 v130, s[58:59]
	s_addc_u32 s45, s59, s7
	s_add_i32 m0, s27, 0x14000
	v_mov_b32_e32 v2, 0
	global_load_lds_dwordx4 v134, s[44:45]
	s_add_i32 m0, s27, 0x16000
	s_add_u32 s56, s22, s28
	s_addc_u32 s57, s23, s29
	s_add_i32 s28, s27, 0x2000
	global_load_lds_dwordx4 v130, s[44:45]
	s_mov_b32 m0, s27
	s_add_u32 s38, s56, s2
	global_load_lds_dwordx4 v136, s[56:57]
	s_mov_b32 m0, s28
	s_addc_u32 s39, s57, s3
	s_add_i32 s29, s27, 0x4000
	global_load_lds_dwordx4 v132, s[56:57]
	s_mov_b32 m0, s29
	s_add_i32 s30, s27, 0x6000
	global_load_lds_dwordx4 v136, s[38:39]
	s_mov_b32 m0, s30
	s_cmpk_lt_u32 s31, 0x100
	global_load_lds_dwordx4 v132, s[38:39]
	s_cselect_b64 s[38:39], -1, 0
	s_cmpk_gt_u32 s31, 0xff
	v_mov_b32_e32 v3, 0
	v_mov_b32_e32 v4, 0
	v_mov_b32_e32 v5, 0
	v_mov_b32_e32 v6, 0
	v_mov_b32_e32 v7, 0
	v_mov_b32_e32 v8, 0
	v_mov_b32_e32 v9, 0
	v_mov_b32_e32 v10, 0
	v_mov_b32_e32 v11, 0
	v_mov_b32_e32 v12, 0
	v_mov_b32_e32 v13, 0
	v_mov_b32_e32 v14, 0
	v_mov_b32_e32 v15, 0
	v_mov_b32_e32 v16, 0
	v_mov_b32_e32 v17, 0
	s_cbranch_scc1 .LBB0_200
	s_lshl_b64 s[40:41], s[54:55], 14
	v_readlane_b32 s47, v236, 63
	s_add_u32 s40, s47, s40
	v_readlane_b32 s47, v235, 0
	s_addc_u32 s41, s47, s41
	v_lshlrev_b64 v[2:3], 6, v[18:19]
	v_lshl_add_u64 v[14:15], s[40:41], 0, v[2:3]
	global_load_dwordx4 v[2:5], v[14:15], off offset:48
	global_load_dwordx4 v[6:9], v[14:15], off offset:32
	global_load_dwordx4 v[10:13], v[14:15], off offset:16
	s_nop 0
	global_load_dwordx4 v[14:17], v[14:15], off
